# v14 + P1 start stagger (16 levels x s_sleep 11 by row-tile index within the XCD)
# baseline (speedup 1.0000x reference)
.LBB0_204:
	s_or_b64 exec, exec, s[0:1]
	v_mov_b32_e32 v8, v214
	s_lshr_b32 s0, s90, 3
	s_and_b32 s0, s0, 15
	s_cmp_eq_u32 s0, 0
	s_cbranch_scc1 .Lstag1_done
.Lstag1_loop:
	s_sleep 11
	s_sub_u32 s0, s0, 1
	s_cmp_lg_u32 s0, 0
	s_cbranch_scc1 .Lstag1_loop
.Lstag1_done:
	s_cmpk_lt_i32 s90, 0xb00
	s_waitcnt lgkmcnt(0)
	s_barrier
	s_cselect_b64 s[2:3], -1, 0
	s_cmpk_gt_i32 s90, 0xaff
	v_readfirstlane_b32 s6, v8
	s_cbranch_scc1 .LBB0_206
	s_ashr_i32 s0, s90, 31
	s_lshr_b32 s0, s0, 29
	s_add_i32 s0, s90, s0
	s_ashr_i32 s1, s0, 3
	s_and_b32 s0, s0, -8
	s_sub_i32 s0, s90, s0
	s_cmp_lt_i32 s0, 0
	s_movk_i32 s4, 0x161
	s_cselect_b32 s4, s4, 0x160
	s_mul_i32 s0, s0, s4
	s_add_i32 s0, s0, s1
	s_mul_hi_i32 s1, s0, 0x2e8ba2e9
	s_lshr_b32 s4, s1, 31
	s_ashr_i32 s1, s1, 5
	s_add_i32 s1, s1, s4
	s_lshl_b32 s4, s1, 3
	s_mulk_i32 s1, 0xb0
	s_sub_i32 s0, s0, s1
	s_sext_i32_i16 s1, s0
	s_bfe_u32 s1, s1, 0x3001c
	s_add_i32 s1, s0, s1
	s_sext_i32_i16 s5, s1
	s_and_b32 s1, s1, 0xfff8
	s_sub_i32 s0, s0, s1
	s_sext_i32_i16 s0, s0
	s_add_i32 s0, s4, s0
	s_ashr_i32 s4, s5, 3
